# A/B items: conv-input tile kept in LDS as f32 (unpacked once at store, two 16-B planes per row), conv loop re-emitted with direct f32 reads and a 1-step software pipeline; static LDS 32 -> 22528
# speedup vs baseline: 1.0092x; 1.0055x over previous
.LBB0_797:
	s_add_i32 s5, s6, s46
	v_mov_b32_e32 v26, v0
	s_cmpk_gt_i32 s5, 0x1ff
	s_cselect_b64 s[34:35], -1, 0
	s_cmpk_lt_i32 s5, 0x200
	v_lshl_add_u32 v26, v26, 4, 32
	s_cselect_b32 s2, s5, s6
	v_add_u32_e32 v27, 0xd800, v26
	s_waitcnt vmcnt(8)
	v_lshrrev_b32_e32 v170, 12, v241
	v_mul_u32_u24_e32 v170, 0xa00, v170
	v_sub_u32_e32 v170, v241, v170
	v_lshlrev_b32_e32 v172, 16, v2
	v_and_b32_e32 v173, 0xffff0000, v2
	v_lshlrev_b32_e32 v174, 16, v3
	v_and_b32_e32 v175, 0xffff0000, v3
	v_lshlrev_b32_e32 v176, 16, v4
	v_and_b32_e32 v177, 0xffff0000, v4
	v_lshlrev_b32_e32 v178, 16, v5
	v_and_b32_e32 v179, 0xffff0000, v5
	ds_write_b128 v170, v[172:175] offset:55328
	ds_write_b128 v170, v[176:179] offset:56096
	v_lshrrev_b32_e32 v151, 12, v245
	v_mul_u32_u24_e32 v151, 0xa00, v151
	v_sub_u32_e32 v151, v245, v151
	v_lshlrev_b32_e32 v182, 16, v6
	v_and_b32_e32 v183, 0xffff0000, v6
	v_lshlrev_b32_e32 v184, 16, v7
	v_and_b32_e32 v185, 0xffff0000, v7
	v_lshlrev_b32_e32 v248, 16, v8
	v_and_b32_e32 v249, 0xffff0000, v8
	v_lshlrev_b32_e32 v250, 16, v9
	v_and_b32_e32 v251, 0xffff0000, v9
	ds_write_b128 v151, v[182:185] offset:55328
	ds_write_b128 v151, v[248:251] offset:56096
	v_lshrrev_b32_e32 v170, 12, v246
	v_mul_u32_u24_e32 v170, 0xa00, v170
	v_sub_u32_e32 v170, v246, v170
	v_lshlrev_b32_e32 v172, 16, v10
	v_and_b32_e32 v173, 0xffff0000, v10
	v_lshlrev_b32_e32 v174, 16, v11
	v_and_b32_e32 v175, 0xffff0000, v11
	v_lshlrev_b32_e32 v176, 16, v12
	v_and_b32_e32 v177, 0xffff0000, v12
	v_lshlrev_b32_e32 v178, 16, v13
	v_and_b32_e32 v179, 0xffff0000, v13
	ds_write_b128 v170, v[172:175] offset:55328
	ds_write_b128 v170, v[176:179] offset:56096
	v_lshrrev_b32_e32 v151, 12, v247
	v_mul_u32_u24_e32 v151, 0xa00, v151
	v_sub_u32_e32 v151, v247, v151
	v_lshlrev_b32_e32 v182, 16, v14
	v_and_b32_e32 v183, 0xffff0000, v14
	v_lshlrev_b32_e32 v184, 16, v15
	v_and_b32_e32 v185, 0xffff0000, v15
	v_lshlrev_b32_e32 v248, 16, v16
	v_and_b32_e32 v249, 0xffff0000, v16
	v_lshlrev_b32_e32 v250, 16, v17
	v_and_b32_e32 v251, 0xffff0000, v17
	ds_write_b128 v151, v[182:185] offset:55328
	ds_write_b128 v151, v[248:251] offset:56096
	v_lshrrev_b32_e32 v170, 12, v252
	v_mul_u32_u24_e32 v170, 0xa00, v170
	v_sub_u32_e32 v170, v252, v170
	v_lshlrev_b32_e32 v172, 16, v18
	v_and_b32_e32 v173, 0xffff0000, v18
	v_lshlrev_b32_e32 v174, 16, v19
	v_and_b32_e32 v175, 0xffff0000, v19
	v_lshlrev_b32_e32 v176, 16, v20
	v_and_b32_e32 v177, 0xffff0000, v20
	v_lshlrev_b32_e32 v178, 16, v21
	v_and_b32_e32 v179, 0xffff0000, v21
	ds_write_b128 v170, v[172:175] offset:55328
	ds_write_b128 v170, v[176:179] offset:56096
	v_lshrrev_b32_e32 v151, 12, v253
	v_mul_u32_u24_e32 v151, 0xa00, v151
	v_sub_u32_e32 v151, v253, v151
	v_lshlrev_b32_e32 v182, 16, v22
	v_and_b32_e32 v183, 0xffff0000, v22
	v_lshlrev_b32_e32 v184, 16, v23
	v_and_b32_e32 v185, 0xffff0000, v23
	v_lshlrev_b32_e32 v248, 16, v24
	v_and_b32_e32 v249, 0xffff0000, v24
	v_lshlrev_b32_e32 v250, 16, v25
	v_and_b32_e32 v251, 0xffff0000, v25
	ds_write_b128 v151, v[182:185] offset:55328
	ds_write_b128 v151, v[248:251] offset:56096
	s_lshl_b32 s7, s2, 5
	s_waitcnt lgkmcnt(0)
	s_barrier
	s_and_b32 s12, s7, 0x7e0
	s_sub_i32 s10, s7, 30
	s_ashr_i32 s11, s10, 31
	s_lshl_b64 s[10:11], s[10:11], 12
	s_add_u32 s10, s60, s10
	s_addc_u32 s11, s61, s11
	s_cmp_eq_u32 s12, 0
	s_cselect_b32 s13, 30, 0
	v_cmp_le_i32_e32 vcc, s13, v234
	v_mov_b32_e32 v2, 0
	v_mov_b32_e32 v3, 0
	v_mov_b32_e32 v4, 0
	v_mov_b32_e32 v5, 0
	s_and_saveexec_b64 s[2:3], vcc
	global_load_dwordx4 v[2:5], v241, s[10:11]
	s_or_b64 exec, exec, s[2:3]
	v_cmp_le_i32_e32 vcc, s13, v235
	v_mov_b32_e32 v6, 0
	v_mov_b32_e32 v7, 0
	v_mov_b32_e32 v8, 0
	v_mov_b32_e32 v9, 0
	s_and_saveexec_b64 s[2:3], vcc
	global_load_dwordx4 v[6:9], v245, s[10:11]
	s_or_b64 exec, exec, s[2:3]
	v_cmp_le_i32_e32 vcc, s13, v236
	v_mov_b32_e32 v10, 0
	v_mov_b32_e32 v11, 0
	v_mov_b32_e32 v12, 0
	v_mov_b32_e32 v13, 0
	s_and_saveexec_b64 s[2:3], vcc
	global_load_dwordx4 v[10:13], v246, s[10:11]
	s_or_b64 exec, exec, s[2:3]
	v_cmp_le_i32_e32 vcc, s13, v237
	v_mov_b32_e32 v14, 0
	v_mov_b32_e32 v15, 0
	v_mov_b32_e32 v16, 0
	v_mov_b32_e32 v17, 0
	s_and_saveexec_b64 s[2:3], vcc
	global_load_dwordx4 v[14:17], v247, s[10:11]
	s_or_b64 exec, exec, s[2:3]
	v_cmp_le_i32_e32 vcc, s13, v238
	v_mov_b32_e32 v18, 0
	v_mov_b32_e32 v19, 0
	v_mov_b32_e32 v20, 0
	v_mov_b32_e32 v21, 0
	s_and_saveexec_b64 s[2:3], vcc
	global_load_dwordx4 v[18:21], v252, s[10:11]
	s_or_b64 exec, exec, s[2:3]
	v_cmp_le_i32_e32 vcc, s13, v239
	v_mov_b32_e32 v22, 0
	v_mov_b32_e32 v23, 0
	v_mov_b32_e32 v24, 0
	v_mov_b32_e32 v25, 0
	s_and_saveexec_b64 s[2:3], vcc
	global_load_dwordx4 v[22:25], v253, s[10:11]
	s_or_b64 exec, exec, s[2:3]
	v_mov_b32_e32 v26, v0
	s_lshl_b32 s2, s6, 5
	v_ashrrev_i32_e32 v152, 6, v26
	v_lshlrev_b32_e32 v150, 2, v152
	v_and_b32_e32 v27, 63, v26
	s_ashr_i32 s3, s2, 31
	v_ashrrev_i32_e32 v151, 31, v150
	v_cmp_gt_u32_e64 s[38:39], 48, v27
	v_lshl_add_u64 v[148:149], v[150:151], 0, s[2:3]
	s_movk_i32 s3, 0x1000
	v_cndmask_b32_e64 v42, 47, v27, s[38:39]
	v_lshlrev_b64 v[26:27], 12, v[148:149]
	v_lshl_add_u64 v[82:83], s[60:61], 0, v[26:27]
	v_lshlrev_b32_e32 v154, 4, v42
	v_lshl_add_u64 v[56:57], v[82:83], 0, v[154:155]
	v_add_co_u32_e32 v26, vcc, s3, v56
	global_load_dwordx4 v[78:81], v[56:57], off offset:768
	global_load_dwordx4 v[38:41], v[56:57], off offset:2304
	v_addc_co_u32_e32 v27, vcc, 0, v57, vcc
	global_load_dwordx4 v[74:77], v[26:27], off offset:768
	global_load_dwordx4 v[34:37], v[26:27], off offset:2304
	v_add_co_u32_e32 v26, vcc, 0x2000, v56
	s_and_b32 s7, s2, 0x7e0
	s_nop 0
	v_addc_co_u32_e32 v27, vcc, 0, v57, vcc
	global_load_dwordx4 v[70:73], v[26:27], off offset:768
	global_load_dwordx4 v[30:33], v[26:27], off offset:2304
	v_add_co_u32_e32 v26, vcc, 0x3000, v56
	v_lshlrev_b32_e32 v86, 3, v42
	s_nop 0
	v_addc_co_u32_e32 v27, vcc, 0, v57, vcc
	global_load_dwordx4 v[58:61], v[26:27], off offset:768
	s_nop 0
	global_load_dwordx4 v[26:29], v[26:27], off offset:2304
	v_add_u32_e32 v63, s7, v150
	v_cmp_lt_i32_e32 vcc, 1, v63
	v_mov_b32_e32 v46, 0
	v_lshlrev_b32_e32 v84, 1, v86
	v_mov_b32_e32 v42, 0
	v_mov_b32_e32 v43, 0
	v_mov_b32_e32 v44, 0
	v_mov_b32_e32 v45, 0
	s_and_saveexec_b64 s[2:3], vcc
	s_cbranch_execz .LBB0_823
	v_mov_b32_e32 v85, v155
	v_lshl_add_u64 v[42:43], v[82:83], 0, v[84:85]
	v_add_co_u32_e32 v42, vcc, 0xfffff000, v42
	s_nop 1
	v_addc_co_u32_e32 v43, vcc, -1, v43, vcc
	global_load_dwordx4 v[42:45], v[42:43], off offset:-2560

.LBB0_833:
	s_or_b64 exec, exec, s[2:3]
	v_lshlrev_b32_e32 v122, 2, v86
	v_mov_b64_e32 v[86:87], v[190:191]
	v_mov_b64_e32 v[88:89], v[192:193]
	v_mov_b64_e32 v[82:83], v[186:187]
	v_mov_b64_e32 v[84:85], v[188:189]
	s_movk_i32 s2, 0x1800
	v_mul_lo_u32 v123, v152, s2
	v_or_b32_e32 v90, v123, v154
	s_add_i32 s2, 32, 0xd800
	v_add_u32_e32 v170, s2, v90
	v_add_u32_e32 v151, 32, v154
	s_mov_b32 s2, -4
	v_mov_b64_e32 v[144:145], v[86:87]
	v_mov_b64_e32 v[140:141], v[82:83]
	v_mov_b64_e32 v[142:143], v[84:85]
	v_mov_b64_e32 v[146:147], v[88:89]
	v_mov_b64_e32 v[132:133], v[82:83]
	v_mov_b64_e32 v[134:135], v[84:85]
	v_mov_b64_e32 v[136:137], v[86:87]
	v_mov_b64_e32 v[138:139], v[88:89]
	v_mov_b64_e32 v[124:125], v[82:83]
	v_mov_b64_e32 v[126:127], v[84:85]
	v_mov_b64_e32 v[128:129], v[86:87]
	v_mov_b64_e32 v[130:131], v[88:89]
	ds_read_b128 v[172:175], v170 offset:0
	ds_read_b128 v[176:179], v170 offset:768
	ds_read_b128 v[114:117], v151 offset:0
	ds_read_b128 v[118:121], v151 offset:768
	s_mov_b32 s2, 0
	ds_read_b128 v[182:185], v170 offset:1536
	ds_read_b128 v[248:251], v170 offset:2304
	s_waitcnt lgkmcnt(4)
	ds_read_b128 v[90:93], v151 offset:1536
	ds_read_b128 v[94:97], v151 offset:2304
	s_waitcnt lgkmcnt(4)
	v_pk_fma_f32 v[82:83], v[114:115], v[172:173], v[82:83]
	v_pk_fma_f32 v[84:85], v[116:117], v[174:175], v[84:85]
	v_pk_fma_f32 v[86:87], v[118:119], v[176:177], v[86:87]
	v_pk_fma_f32 v[88:89], v[120:121], v[178:179], v[88:89]
	ds_read_b128 v[172:175], v170 offset:3072
	ds_read_b128 v[176:179], v170 offset:3840
	s_waitcnt lgkmcnt(4)
	ds_read_b128 v[98:101], v151 offset:3072
	ds_read_b128 v[102:105], v151 offset:3840
	v_pk_fma_f32 v[140:141], v[114:115], v[182:183], v[140:141]
	v_pk_fma_f32 v[142:143], v[116:117], v[184:185], v[142:143]
	v_pk_fma_f32 v[144:145], v[118:119], v[248:249], v[144:145]
	v_pk_fma_f32 v[146:147], v[120:121], v[250:251], v[146:147]
	s_waitcnt lgkmcnt(4)
	v_pk_fma_f32 v[82:83], v[90:91], v[182:183], v[82:83]
	v_pk_fma_f32 v[84:85], v[92:93], v[184:185], v[84:85]
	v_pk_fma_f32 v[86:87], v[94:95], v[248:249], v[86:87]
	v_pk_fma_f32 v[88:89], v[96:97], v[250:251], v[88:89]
	ds_read_b128 v[182:185], v170 offset:4608
	ds_read_b128 v[248:251], v170 offset:5376
	s_waitcnt lgkmcnt(4)
	ds_read_b128 v[106:109], v151 offset:4608
	ds_read_b128 v[110:113], v151 offset:5376
	v_pk_fma_f32 v[132:133], v[114:115], v[172:173], v[132:133]
	v_pk_fma_f32 v[134:135], v[116:117], v[174:175], v[134:135]
	v_pk_fma_f32 v[136:137], v[118:119], v[176:177], v[136:137]
	v_pk_fma_f32 v[138:139], v[120:121], v[178:179], v[138:139]
	v_pk_fma_f32 v[140:141], v[90:91], v[172:173], v[140:141]
	v_pk_fma_f32 v[142:143], v[92:93], v[174:175], v[142:143]
	v_pk_fma_f32 v[144:145], v[94:95], v[176:177], v[144:145]
	v_pk_fma_f32 v[146:147], v[96:97], v[178:179], v[146:147]
	s_waitcnt lgkmcnt(4)
	v_pk_fma_f32 v[82:83], v[98:99], v[172:173], v[82:83]
	v_pk_fma_f32 v[84:85], v[100:101], v[174:175], v[84:85]
	v_pk_fma_f32 v[86:87], v[102:103], v[176:177], v[86:87]
	v_pk_fma_f32 v[88:89], v[104:105], v[178:179], v[88:89]
	ds_read_b128 v[172:175], v170 offset:6144
	ds_read_b128 v[176:179], v170 offset:6912
	s_waitcnt lgkmcnt(4)
	v_pk_fma_f32 v[124:125], v[114:115], v[182:183], v[124:125]
	v_pk_fma_f32 v[126:127], v[116:117], v[184:185], v[126:127]
	v_pk_fma_f32 v[128:129], v[118:119], v[248:249], v[128:129]
	v_pk_fma_f32 v[130:131], v[120:121], v[250:251], v[130:131]
	ds_read_b128 v[114:117], v151 offset:6144
	ds_read_b128 v[118:121], v151 offset:6912
	v_pk_fma_f32 v[132:133], v[90:91], v[182:183], v[132:133]
	v_pk_fma_f32 v[134:135], v[92:93], v[184:185], v[134:135]
	v_pk_fma_f32 v[136:137], v[94:95], v[248:249], v[136:137]
	v_pk_fma_f32 v[138:139], v[96:97], v[250:251], v[138:139]
	v_pk_fma_f32 v[140:141], v[98:99], v[182:183], v[140:141]
	v_pk_fma_f32 v[142:143], v[100:101], v[184:185], v[142:143]
	v_pk_fma_f32 v[144:145], v[102:103], v[248:249], v[144:145]
	v_pk_fma_f32 v[146:147], v[104:105], v[250:251], v[146:147]
	s_waitcnt lgkmcnt(4)
	v_pk_fma_f32 v[82:83], v[106:107], v[182:183], v[82:83]
	v_pk_fma_f32 v[84:85], v[108:109], v[184:185], v[84:85]
	v_pk_fma_f32 v[86:87], v[110:111], v[248:249], v[86:87]
	v_pk_fma_f32 v[88:89], v[112:113], v[250:251], v[88:89]
	v_add_u32_e32 v151, 0x1800, v151
	v_add_u32_e32 v170, 0x1800, v170
.LCV_loop:
	ds_read_b128 v[182:185], v170 offset:1536
	ds_read_b128 v[248:251], v170 offset:2304
	s_waitcnt lgkmcnt(4)
	v_pk_fma_f32 v[124:125], v[90:91], v[172:173], v[124:125]
	v_pk_fma_f32 v[126:127], v[92:93], v[174:175], v[126:127]
	v_pk_fma_f32 v[128:129], v[94:95], v[176:177], v[128:129]
	v_pk_fma_f32 v[130:131], v[96:97], v[178:179], v[130:131]
	ds_read_b128 v[90:93], v151 offset:1536
	ds_read_b128 v[94:97], v151 offset:2304
	v_pk_fma_f32 v[132:133], v[98:99], v[172:173], v[132:133]
	v_pk_fma_f32 v[134:135], v[100:101], v[174:175], v[134:135]
	v_pk_fma_f32 v[136:137], v[102:103], v[176:177], v[136:137]
	v_pk_fma_f32 v[138:139], v[104:105], v[178:179], v[138:139]
	v_pk_fma_f32 v[140:141], v[106:107], v[172:173], v[140:141]
	v_pk_fma_f32 v[142:143], v[108:109], v[174:175], v[142:143]
	v_pk_fma_f32 v[144:145], v[110:111], v[176:177], v[144:145]
	v_pk_fma_f32 v[146:147], v[112:113], v[178:179], v[146:147]
	s_waitcnt lgkmcnt(4)
	v_pk_fma_f32 v[82:83], v[114:115], v[172:173], v[82:83]
	v_pk_fma_f32 v[84:85], v[116:117], v[174:175], v[84:85]
	v_pk_fma_f32 v[86:87], v[118:119], v[176:177], v[86:87]
	v_pk_fma_f32 v[88:89], v[120:121], v[178:179], v[88:89]
	ds_read_b128 v[172:175], v170 offset:3072
	ds_read_b128 v[176:179], v170 offset:3840
	s_waitcnt lgkmcnt(4)
	v_pk_fma_f32 v[124:125], v[98:99], v[182:183], v[124:125]
	v_pk_fma_f32 v[126:127], v[100:101], v[184:185], v[126:127]
	v_pk_fma_f32 v[128:129], v[102:103], v[248:249], v[128:129]
	v_pk_fma_f32 v[130:131], v[104:105], v[250:251], v[130:131]
	ds_read_b128 v[98:101], v151 offset:3072
	ds_read_b128 v[102:105], v151 offset:3840
	v_pk_fma_f32 v[132:133], v[106:107], v[182:183], v[132:133]
	v_pk_fma_f32 v[134:135], v[108:109], v[184:185], v[134:135]
	v_pk_fma_f32 v[136:137], v[110:111], v[248:249], v[136:137]
	v_pk_fma_f32 v[138:139], v[112:113], v[250:251], v[138:139]
	v_pk_fma_f32 v[140:141], v[114:115], v[182:183], v[140:141]
	v_pk_fma_f32 v[142:143], v[116:117], v[184:185], v[142:143]
	v_pk_fma_f32 v[144:145], v[118:119], v[248:249], v[144:145]
	v_pk_fma_f32 v[146:147], v[120:121], v[250:251], v[146:147]
	s_waitcnt lgkmcnt(4)
	v_pk_fma_f32 v[82:83], v[90:91], v[182:183], v[82:83]
	v_pk_fma_f32 v[84:85], v[92:93], v[184:185], v[84:85]
	v_pk_fma_f32 v[86:87], v[94:95], v[248:249], v[86:87]
	v_pk_fma_f32 v[88:89], v[96:97], v[250:251], v[88:89]
	ds_read_b128 v[182:185], v170 offset:4608
	ds_read_b128 v[248:251], v170 offset:5376
	s_waitcnt lgkmcnt(4)
	v_pk_fma_f32 v[124:125], v[106:107], v[172:173], v[124:125]
	v_pk_fma_f32 v[126:127], v[108:109], v[174:175], v[126:127]
	v_pk_fma_f32 v[128:129], v[110:111], v[176:177], v[128:129]
	v_pk_fma_f32 v[130:131], v[112:113], v[178:179], v[130:131]
	ds_read_b128 v[106:109], v151 offset:4608
	ds_read_b128 v[110:113], v151 offset:5376
	v_pk_fma_f32 v[132:133], v[114:115], v[172:173], v[132:133]
	v_pk_fma_f32 v[134:135], v[116:117], v[174:175], v[134:135]
	v_pk_fma_f32 v[136:137], v[118:119], v[176:177], v[136:137]
	v_pk_fma_f32 v[138:139], v[120:121], v[178:179], v[138:139]
	v_pk_fma_f32 v[140:141], v[90:91], v[172:173], v[140:141]
	v_pk_fma_f32 v[142:143], v[92:93], v[174:175], v[142:143]
	v_pk_fma_f32 v[144:145], v[94:95], v[176:177], v[144:145]
	v_pk_fma_f32 v[146:147], v[96:97], v[178:179], v[146:147]
	s_waitcnt lgkmcnt(4)
	v_pk_fma_f32 v[82:83], v[98:99], v[172:173], v[82:83]
	v_pk_fma_f32 v[84:85], v[100:101], v[174:175], v[84:85]
	v_pk_fma_f32 v[86:87], v[102:103], v[176:177], v[86:87]
	v_pk_fma_f32 v[88:89], v[104:105], v[178:179], v[88:89]
	ds_read_b128 v[172:175], v170 offset:6144
	ds_read_b128 v[176:179], v170 offset:6912
	s_waitcnt lgkmcnt(4)
	v_pk_fma_f32 v[124:125], v[114:115], v[182:183], v[124:125]
	v_pk_fma_f32 v[126:127], v[116:117], v[184:185], v[126:127]
	v_pk_fma_f32 v[128:129], v[118:119], v[248:249], v[128:129]
	v_pk_fma_f32 v[130:131], v[120:121], v[250:251], v[130:131]
	ds_read_b128 v[114:117], v151 offset:6144
	ds_read_b128 v[118:121], v151 offset:6912
	v_pk_fma_f32 v[132:133], v[90:91], v[182:183], v[132:133]
	v_pk_fma_f32 v[134:135], v[92:93], v[184:185], v[134:135]
	v_pk_fma_f32 v[136:137], v[94:95], v[248:249], v[136:137]
	v_pk_fma_f32 v[138:139], v[96:97], v[250:251], v[138:139]
	v_pk_fma_f32 v[140:141], v[98:99], v[182:183], v[140:141]
	v_pk_fma_f32 v[142:143], v[100:101], v[184:185], v[142:143]
	v_pk_fma_f32 v[144:145], v[102:103], v[248:249], v[144:145]
	v_pk_fma_f32 v[146:147], v[104:105], v[250:251], v[146:147]
	s_waitcnt lgkmcnt(4)
	v_pk_fma_f32 v[82:83], v[106:107], v[182:183], v[82:83]
	v_pk_fma_f32 v[84:85], v[108:109], v[184:185], v[84:85]
	v_pk_fma_f32 v[86:87], v[110:111], v[248:249], v[86:87]
	v_pk_fma_f32 v[88:89], v[112:113], v[250:251], v[88:89]
	v_add_u32_e32 v151, 0x1800, v151
	v_add_u32_e32 v170, 0x1800, v170
	s_add_i32 s2, s2, 4
	s_cmp_gt_u32 s2, 27
	s_cbranch_scc0 .LCV_loop
	ds_read_b128 v[182:185], v170 offset:1536
	ds_read_b128 v[248:251], v170 offset:2304
	s_waitcnt lgkmcnt(4)
	v_pk_fma_f32 v[132:133], v[98:99], v[172:173], v[132:133]
	v_pk_fma_f32 v[134:135], v[100:101], v[174:175], v[134:135]
	v_pk_fma_f32 v[136:137], v[102:103], v[176:177], v[136:137]
	v_pk_fma_f32 v[138:139], v[104:105], v[178:179], v[138:139]
	v_pk_fma_f32 v[124:125], v[90:91], v[172:173], v[124:125]
	v_pk_fma_f32 v[126:127], v[92:93], v[174:175], v[126:127]
	v_pk_fma_f32 v[128:129], v[94:95], v[176:177], v[128:129]
	v_pk_fma_f32 v[130:131], v[96:97], v[178:179], v[130:131]
	s_waitcnt lgkmcnt(0)
	v_pk_fma_f32 v[124:125], v[98:99], v[182:183], v[124:125]
	v_pk_fma_f32 v[126:127], v[100:101], v[184:185], v[126:127]
	v_pk_fma_f32 v[128:129], v[102:103], v[248:249], v[128:129]
	v_pk_fma_f32 v[130:131], v[104:105], v[250:251], v[130:131]
	s_waitcnt vmcnt(0)
	v_mov_b32_e32 v149, v66
	v_mov_b32_e32 v153, v67
	v_mov_b32_e32 v164, v68
	v_mov_b32_e32 v165, v69
	v_mov_b32_e32 v166, v62
	v_mov_b32_e32 v167, v63
	v_mov_b32_e32 v168, v64
	v_mov_b32_e32 v169, v65
	s_ashr_i32 s6, s6, 6
	s_cmpk_eq_i32 s7, 0x7e0
	s_cselect_b64 s[36:37], -1, 0
	s_and_b64 s[2:3], s[36:37], s[38:39]
	s_and_saveexec_b64 s[10:11], s[2:3]
	s_cbranch_execz .LBB0_840
	v_add_u32_e32 v90, 32, v123
	s_mov_b32 s2, 0xd800
	v_add3_u32 v90, v90, v154, s2
	s_add_i32 s2, s6, s4
	s_mul_i32 s12, s2, 30
	s_ashr_i32 s13, s12, 31
	v_cmp_lt_i32_e32 vcc, 0, v152
	s_and_saveexec_b64 s[2:3], vcc
	s_cbranch_execz .LBB0_838
	v_readlane_b32 s16, v243, 31
	v_add_u32_e32 v92, -2, v150
	v_mov_b32_e32 v93, v155
	v_readlane_b32 s17, v243, 32
	v_lshl_add_u64 v[92:93], v[92:93], 0, s[12:13]
	s_movk_i32 s7, 0x600
	v_mov_b64_e32 v[104:105], s[16:17]
	v_mad_u64_u32 v[94:95], s[16:17], v92, s7, v[104:105]
	v_mad_i32_i24 v95, v93, s7, v95
	v_mov_b32_e32 v123, v155
	v_lshl_add_u64 v[106:107], v[94:95], 0, v[122:123]
	ds_read_b128 v[96:99], v90 offset:46080
	ds_read_b128 v[100:103], v90 offset:46848
	s_waitcnt lgkmcnt(0)
	v_add_u32_e32 v92, -1, v150
	v_mov_b32_e32 v93, v155
	v_lshl_add_u64 v[92:93], v[92:93], 0, s[12:13]
	v_mad_u64_u32 v[94:95], s[16:17], v92, s7, v[104:105]
	global_store_dwordx4 v[106:107], v[100:103], off offset:16
	global_store_dwordx4 v[106:107], v[96:99], off
	v_mad_i32_i24 v95, v93, s7, v95
	v_lshl_add_u64 v[104:105], v[94:95], 0, v[122:123]
	ds_read_b128 v[96:99], v90 offset:47616
	ds_read_b128 v[100:103], v90 offset:48384
	s_waitcnt lgkmcnt(0)
	global_store_dwordx4 v[104:105], v[100:103], off offset:16
	global_store_dwordx4 v[104:105], v[96:99], off
.LBB0_838:
	s_or_b64 exec, exec, s[2:3]
	v_cmp_lt_i32_e32 vcc, -1, v152
	s_and_b64 exec, exec, vcc
	s_cbranch_execz .LBB0_840
	v_readlane_b32 s2, v243, 31
	v_mov_b32_e32 v151, v155
	v_readlane_b32 s3, v243, 32
	v_lshl_add_u64 v[92:93], v[150:151], 0, s[12:13]
	s_movk_i32 s7, 0x600
	v_mov_b64_e32 v[104:105], s[2:3]
	v_mad_u64_u32 v[94:95], s[2:3], v92, s7, v[104:105]
	v_mad_i32_i24 v95, v93, s7, v95
	v_mov_b32_e32 v123, v155
	v_lshl_add_u64 v[106:107], v[94:95], 0, v[122:123]
	ds_read_b128 v[96:99], v90 offset:49152
	ds_read_b128 v[100:103], v90 offset:49920
	s_waitcnt lgkmcnt(0)
	v_or_b32_e32 v92, 1, v150
	v_mov_b32_e32 v93, v155
	v_lshl_add_u64 v[92:93], v[92:93], 0, s[12:13]
	global_store_dwordx4 v[106:107], v[100:103], off offset:16
	global_store_dwordx4 v[106:107], v[96:99], off
	v_mad_u64_u32 v[94:95], s[2:3], v92, s7, v[104:105]
	v_mad_i32_i24 v95, v93, s7, v95
	v_lshl_add_u64 v[102:103], v[94:95], 0, v[122:123]
	ds_read_b128 v[94:97], v90 offset:50688
	ds_read_b128 v[98:101], v90 offset:51456
	s_waitcnt lgkmcnt(0)
	global_store_dwordx4 v[102:103], v[98:101], off offset:16
	global_store_dwordx4 v[102:103], v[94:97], off

	.amdhsa_kernel _Z14fwd_megakernel6Params
		.amdhsa_group_segment_fixed_size 22528
		.amdhsa_private_segment_fixed_size 0
		.amdhsa_kernarg_size 472
		.amdhsa_user_sgpr_count 2
		.amdhsa_user_sgpr_dispatch_ptr 0
		.amdhsa_user_sgpr_queue_ptr 0
		.amdhsa_user_sgpr_kernarg_segment_ptr 1
		.amdhsa_user_sgpr_dispatch_id 0
		.amdhsa_user_sgpr_kernarg_preload_length 0
		.amdhsa_user_sgpr_kernarg_preload_offset 0
		.amdhsa_user_sgpr_private_segment_size 0
		.amdhsa_uses_dynamic_stack 0
		.amdhsa_enable_private_segment 0
		.amdhsa_system_sgpr_workgroup_id_x 1
		.amdhsa_system_sgpr_workgroup_id_y 0
		.amdhsa_system_sgpr_workgroup_id_z 0
		.amdhsa_system_sgpr_workgroup_info 0
		.amdhsa_system_vgpr_workitem_id 0
		.amdhsa_next_free_vgpr 256
		.amdhsa_next_free_sgpr 102
		.amdhsa_accum_offset 256
		.amdhsa_reserve_vcc 1
		.amdhsa_float_round_mode_32 0
		.amdhsa_float_round_mode_16_64 0
		.amdhsa_float_denorm_mode_32 3
		.amdhsa_float_denorm_mode_16_64 3
		.amdhsa_dx10_clamp 1
		.amdhsa_ieee_mode 1
		.amdhsa_fp16_overflow 0
		.amdhsa_tg_split 0
		.amdhsa_exception_fp_ieee_invalid_op 0
		.amdhsa_exception_fp_denorm_src 0
		.amdhsa_exception_fp_ieee_div_zero 0
		.amdhsa_exception_fp_ieee_overflow 0
		.amdhsa_exception_fp_ieee_underflow 0
		.amdhsa_exception_fp_ieee_inexact 0
		.amdhsa_exception_int_div_zero 0
	.end_amdhsa_kernel

amdhsa.kernels:
  - .agpr_count:     0
    .args:
      - .offset:         0
        .size:           216
        .value_kind:     by_value
      - .offset:         216
        .size:           4
        .value_kind:     hidden_block_count_x
      - .offset:         220
        .size:           4
        .value_kind:     hidden_block_count_y
      - .offset:         224
        .size:           4
        .value_kind:     hidden_block_count_z
      - .offset:         228
        .size:           2
        .value_kind:     hidden_group_size_x
      - .offset:         230
        .size:           2
        .value_kind:     hidden_group_size_y
      - .offset:         232
        .size:           2
        .value_kind:     hidden_group_size_z
      - .offset:         234
        .size:           2
        .value_kind:     hidden_remainder_x
      - .offset:         236
        .size:           2
        .value_kind:     hidden_remainder_y
      - .offset:         238
        .size:           2
        .value_kind:     hidden_remainder_z
      - .offset:         256
        .size:           8
        .value_kind:     hidden_global_offset_x
      - .offset:         264
        .size:           8
        .value_kind:     hidden_global_offset_y
      - .offset:         272
        .size:           8
        .value_kind:     hidden_global_offset_z
      - .offset:         280
        .size:           2
        .value_kind:     hidden_grid_dims
      - .offset:         336
        .size:           4
        .value_kind:     hidden_dynamic_lds_size
    .group_segment_fixed_size: 22528
    .kernarg_segment_align: 8
    .kernarg_segment_size: 472
    .language:       OpenCL C
    .language_version:
      - 2
      - 0
    .max_flat_workgroup_size: 512
    .name:           _Z14fwd_megakernel6Params
    .private_segment_fixed_size: 0
    .sgpr_count:     108
    .sgpr_spill_count: 192
    .symbol:         _Z14fwd_megakernel6Params.kd
    .uniform_work_group_size: 1
    .uses_dynamic_stack: false
    .vgpr_count:     256
    .vgpr_spill_count: 0
    .wavefront_size: 64
